# column-maximum pass over w_in (kernel start): the 64 strided loads per task, previously issued two at a time behind vmcnt(1)/(0) with a NaN bail-out ladder, are issued 48+16 in flight and reduced with
# speedup vs baseline: 1.0173x; 1.0110x over previous
; __global__ void __launch_bounds__(512, 2) fwd_kernel(Args a) {
;     ...
;     for (int tk = gw; tk < 4 * 144 * 16; tk += NGW) { const int l4 = tk / (144 * 16), cg = (tk >> 4) % 144, kc = tk & 15, c = 64 * cg + lane;
;         const int drow = win_dest_row(c), slot = drow >= 7168 ? -2 : pg8::p1_qslot(__builtin_amdgcn_readfirstlane(drow) >> 8);
;         if (slot == -1) continue;
;         const float* wp = a.in[2] + (size_t)l4 * DM * NIN + (size_t)(64 * kc) * NIN + c; float mx = 0.f;
; #pragma unroll 32
;         for (int kk = 0; kk < 64; ++kk) mx = fmaxf(mx, fabsf(wp[(size_t)kk * NIN]));
.LBB0_29:
	s_or_b64 exec, exec, s[4:5]
	v_cmp_ne_u32_e32 vcc, -1, v5
	s_and_saveexec_b64 s[4:5], vcc
	s_cbranch_execz .LBB0_10
	s_mul_hi_i32 s6, s85, 0x38e38e39
	s_lshr_b32 s7, s6, 31
	s_ashr_i32 s86, s6, 9
	s_add_i32 s86, s86, s7
	v_readlane_b32 s12, v252, 17
	s_mul_i32 s88, s86, 0x2400000
	v_readlane_b32 s16, v252, 21
	s_mul_hi_i32 s87, s86, 0x2400000
	v_readlane_b32 s17, v252, 22
	s_add_u32 s6, s16, s88
	s_addc_u32 s7, s17, s87
	s_lshl_b32 s10, s85, 6
	s_and_b32 s10, s10, 0x3c0
	s_mul_i32 s10, s10, 0x9000
	s_add_u32 s6, s6, s10
	s_addc_u32 s7, s7, 0
	v_ashrrev_i32_e32 v9, 31, v8
	v_lshl_add_u64 v[6:7], v[8:9], 2, s[6:7]
	s_mov_b64 s[98:99], 0x9000
	v_mov_b32_e32 v10, v6
	v_mov_b32_e32 v11, v7
	global_load_dword v120, v[10:11], off
	v_lshl_add_u64 v[10:11], v[10:11], 0, s[98:99]
	global_load_dword v121, v[10:11], off
	v_lshl_add_u64 v[10:11], v[10:11], 0, s[98:99]
	global_load_dword v122, v[10:11], off
	v_lshl_add_u64 v[10:11], v[10:11], 0, s[98:99]
	global_load_dword v123, v[10:11], off
	v_lshl_add_u64 v[10:11], v[10:11], 0, s[98:99]
	global_load_dword v124, v[10:11], off
	v_lshl_add_u64 v[10:11], v[10:11], 0, s[98:99]
	global_load_dword v125, v[10:11], off
	v_lshl_add_u64 v[10:11], v[10:11], 0, s[98:99]
	global_load_dword v126, v[10:11], off
	v_lshl_add_u64 v[10:11], v[10:11], 0, s[98:99]
	global_load_dword v127, v[10:11], off
	v_lshl_add_u64 v[10:11], v[10:11], 0, s[98:99]
	global_load_dword v128, v[10:11], off
	v_lshl_add_u64 v[10:11], v[10:11], 0, s[98:99]
	global_load_dword v129, v[10:11], off
	v_lshl_add_u64 v[10:11], v[10:11], 0, s[98:99]
	global_load_dword v130, v[10:11], off
	v_lshl_add_u64 v[10:11], v[10:11], 0, s[98:99]
	global_load_dword v131, v[10:11], off
	v_lshl_add_u64 v[10:11], v[10:11], 0, s[98:99]
	global_load_dword v132, v[10:11], off
	v_lshl_add_u64 v[10:11], v[10:11], 0, s[98:99]
	global_load_dword v133, v[10:11], off
	v_lshl_add_u64 v[10:11], v[10:11], 0, s[98:99]
	global_load_dword v134, v[10:11], off
	v_lshl_add_u64 v[10:11], v[10:11], 0, s[98:99]
	global_load_dword v135, v[10:11], off
	v_lshl_add_u64 v[10:11], v[10:11], 0, s[98:99]
	global_load_dword v136, v[10:11], off
	v_lshl_add_u64 v[10:11], v[10:11], 0, s[98:99]
	global_load_dword v137, v[10:11], off
	v_lshl_add_u64 v[10:11], v[10:11], 0, s[98:99]
	global_load_dword v138, v[10:11], off
	v_lshl_add_u64 v[10:11], v[10:11], 0, s[98:99]
	global_load_dword v139, v[10:11], off
	v_lshl_add_u64 v[10:11], v[10:11], 0, s[98:99]
	global_load_dword v140, v[10:11], off
	v_lshl_add_u64 v[10:11], v[10:11], 0, s[98:99]
	global_load_dword v141, v[10:11], off
	v_lshl_add_u64 v[10:11], v[10:11], 0, s[98:99]
	global_load_dword v142, v[10:11], off
	v_lshl_add_u64 v[10:11], v[10:11], 0, s[98:99]
	global_load_dword v143, v[10:11], off
	v_lshl_add_u64 v[10:11], v[10:11], 0, s[98:99]
	global_load_dword v144, v[10:11], off
	v_lshl_add_u64 v[10:11], v[10:11], 0, s[98:99]
	global_load_dword v145, v[10:11], off
	v_lshl_add_u64 v[10:11], v[10:11], 0, s[98:99]
	global_load_dword v146, v[10:11], off
	v_lshl_add_u64 v[10:11], v[10:11], 0, s[98:99]
	global_load_dword v147, v[10:11], off
	v_lshl_add_u64 v[10:11], v[10:11], 0, s[98:99]
	global_load_dword v148, v[10:11], off
	v_lshl_add_u64 v[10:11], v[10:11], 0, s[98:99]
	global_load_dword v149, v[10:11], off
	v_lshl_add_u64 v[10:11], v[10:11], 0, s[98:99]
	global_load_dword v150, v[10:11], off
	v_lshl_add_u64 v[10:11], v[10:11], 0, s[98:99]
	global_load_dword v151, v[10:11], off
	v_lshl_add_u64 v[10:11], v[10:11], 0, s[98:99]
	global_load_dword v152, v[10:11], off
	v_lshl_add_u64 v[10:11], v[10:11], 0, s[98:99]
	global_load_dword v153, v[10:11], off
	v_lshl_add_u64 v[10:11], v[10:11], 0, s[98:99]
	global_load_dword v154, v[10:11], off
	v_lshl_add_u64 v[10:11], v[10:11], 0, s[98:99]
	global_load_dword v155, v[10:11], off
	v_lshl_add_u64 v[10:11], v[10:11], 0, s[98:99]
	global_load_dword v156, v[10:11], off
	v_lshl_add_u64 v[10:11], v[10:11], 0, s[98:99]
	global_load_dword v157, v[10:11], off
	v_lshl_add_u64 v[10:11], v[10:11], 0, s[98:99]
	global_load_dword v158, v[10:11], off
	v_lshl_add_u64 v[10:11], v[10:11], 0, s[98:99]
	global_load_dword v159, v[10:11], off
	v_lshl_add_u64 v[10:11], v[10:11], 0, s[98:99]
	global_load_dword v160, v[10:11], off
	v_lshl_add_u64 v[10:11], v[10:11], 0, s[98:99]
	global_load_dword v161, v[10:11], off
	v_lshl_add_u64 v[10:11], v[10:11], 0, s[98:99]
	global_load_dword v162, v[10:11], off
	v_lshl_add_u64 v[10:11], v[10:11], 0, s[98:99]
	global_load_dword v163, v[10:11], off
	v_lshl_add_u64 v[10:11], v[10:11], 0, s[98:99]
	global_load_dword v164, v[10:11], off
	v_lshl_add_u64 v[10:11], v[10:11], 0, s[98:99]
	global_load_dword v165, v[10:11], off
	v_lshl_add_u64 v[10:11], v[10:11], 0, s[98:99]
	global_load_dword v166, v[10:11], off
	v_lshl_add_u64 v[10:11], v[10:11], 0, s[98:99]
	global_load_dword v167, v[10:11], off
	v_lshl_add_u64 v[10:11], v[10:11], 0, s[98:99]
	v_readlane_b32 s13, v252, 18
	v_readlane_b32 s14, v252, 19
	v_readlane_b32 s15, v252, 20
	v_readlane_b32 s18, v252, 23
	v_readlane_b32 s19, v252, 24
	v_readlane_b32 s20, v252, 25
	v_readlane_b32 s21, v252, 26
	v_readlane_b32 s22, v252, 27
	v_readlane_b32 s23, v252, 28
	v_readlane_b32 s24, v252, 29
	v_readlane_b32 s25, v252, 30
	v_readlane_b32 s26, v252, 31
	v_readlane_b32 s27, v252, 32
	v_mov_b32_e32 v12, 0
	v_mov_b32_e32 v13, 0
	s_waitcnt vmcnt(32)
; __global__ void __launch_bounds__(512, 2) fwd_kernel(Args a) {
;     ...
;         const float* wp = a.in[2] + (size_t)l4 * DM * NIN + (size_t)(64 * kc) * NIN + c; float mx = 0.f;
; #pragma unroll 32
;         for (int kk = 0; kk < 64; ++kk) mx = fmaxf(mx, fabsf(wp[(size_t)kk * NIN]));
;         unsigned* dst = slot == -2 ? (unsigned*)(a.ws + WS_CMAX) + l4 * 2048 + (drow - 7168) : (unsigned*)(a.ws + WS_CMAX1) + l4 * (pg8::P1_NQ * 256) + slot * 256 + (drow & 255);
;         atomicMax(dst, __float_as_uint(mx)); }
	v_max_f32_e64 v14, |v120|, |v120|
	v_max_f32_e32 v12, v12, v14
	v_max_f32_e64 v15, |v121|, |v121|
	v_max_f32_e32 v13, v13, v15
	v_max_f32_e64 v14, |v122|, |v122|
	v_max_f32_e32 v12, v12, v14
	v_max_f32_e64 v15, |v123|, |v123|
	v_max_f32_e32 v13, v13, v15
	v_max_f32_e64 v14, |v124|, |v124|
	v_max_f32_e32 v12, v12, v14
	v_max_f32_e64 v15, |v125|, |v125|
	v_max_f32_e32 v13, v13, v15
	v_max_f32_e64 v14, |v126|, |v126|
	v_max_f32_e32 v12, v12, v14
	v_max_f32_e64 v15, |v127|, |v127|
	v_max_f32_e32 v13, v13, v15
	v_max_f32_e64 v14, |v128|, |v128|
	v_max_f32_e32 v12, v12, v14
	v_max_f32_e64 v15, |v129|, |v129|
	v_max_f32_e32 v13, v13, v15
	v_max_f32_e64 v14, |v130|, |v130|
	v_max_f32_e32 v12, v12, v14
	v_max_f32_e64 v15, |v131|, |v131|
	v_max_f32_e32 v13, v13, v15
	v_max_f32_e64 v14, |v132|, |v132|
	v_max_f32_e32 v12, v12, v14
	v_max_f32_e64 v15, |v133|, |v133|
	v_max_f32_e32 v13, v13, v15
	v_max_f32_e64 v14, |v134|, |v134|
	v_max_f32_e32 v12, v12, v14
	v_max_f32_e64 v15, |v135|, |v135|
	v_max_f32_e32 v13, v13, v15
	global_load_dword v168, v[10:11], off
	v_lshl_add_u64 v[10:11], v[10:11], 0, s[98:99]
	global_load_dword v169, v[10:11], off
	v_lshl_add_u64 v[10:11], v[10:11], 0, s[98:99]
	global_load_dword v170, v[10:11], off
	v_lshl_add_u64 v[10:11], v[10:11], 0, s[98:99]
	global_load_dword v171, v[10:11], off
	v_lshl_add_u64 v[10:11], v[10:11], 0, s[98:99]
	global_load_dword v172, v[10:11], off
	v_lshl_add_u64 v[10:11], v[10:11], 0, s[98:99]
	global_load_dword v173, v[10:11], off
	v_lshl_add_u64 v[10:11], v[10:11], 0, s[98:99]
	global_load_dword v174, v[10:11], off
	v_lshl_add_u64 v[10:11], v[10:11], 0, s[98:99]
	global_load_dword v175, v[10:11], off
	v_lshl_add_u64 v[10:11], v[10:11], 0, s[98:99]
	global_load_dword v176, v[10:11], off
	v_lshl_add_u64 v[10:11], v[10:11], 0, s[98:99]
	global_load_dword v177, v[10:11], off
	v_lshl_add_u64 v[10:11], v[10:11], 0, s[98:99]
	global_load_dword v178, v[10:11], off
	v_lshl_add_u64 v[10:11], v[10:11], 0, s[98:99]
	global_load_dword v179, v[10:11], off
	v_lshl_add_u64 v[10:11], v[10:11], 0, s[98:99]
	global_load_dword v180, v[10:11], off
	v_lshl_add_u64 v[10:11], v[10:11], 0, s[98:99]
	global_load_dword v181, v[10:11], off
	v_lshl_add_u64 v[10:11], v[10:11], 0, s[98:99]
	global_load_dword v182, v[10:11], off
	v_lshl_add_u64 v[10:11], v[10:11], 0, s[98:99]
	global_load_dword v183, v[10:11], off
	v_lshl_add_u64 v[10:11], v[10:11], 0, s[98:99]
	s_waitcnt vmcnt(32)
	v_max_f32_e64 v14, |v136|, |v136|
	v_max_f32_e32 v12, v12, v14
	v_max_f32_e64 v15, |v137|, |v137|
	v_max_f32_e32 v13, v13, v15
	v_max_f32_e64 v14, |v138|, |v138|
	v_max_f32_e32 v12, v12, v14
	v_max_f32_e64 v15, |v139|, |v139|
	v_max_f32_e32 v13, v13, v15
	v_max_f32_e64 v14, |v140|, |v140|
	v_max_f32_e32 v12, v12, v14
	v_max_f32_e64 v15, |v141|, |v141|
	v_max_f32_e32 v13, v13, v15
	v_max_f32_e64 v14, |v142|, |v142|
	v_max_f32_e32 v12, v12, v14
	v_max_f32_e64 v15, |v143|, |v143|
	v_max_f32_e32 v13, v13, v15
	v_max_f32_e64 v14, |v144|, |v144|
	v_max_f32_e32 v12, v12, v14
	v_max_f32_e64 v15, |v145|, |v145|
	v_max_f32_e32 v13, v13, v15
	v_max_f32_e64 v14, |v146|, |v146|
	v_max_f32_e32 v12, v12, v14
	v_max_f32_e64 v15, |v147|, |v147|
	v_max_f32_e32 v13, v13, v15
	v_max_f32_e64 v14, |v148|, |v148|
	v_max_f32_e32 v12, v12, v14
	v_max_f32_e64 v15, |v149|, |v149|
	v_max_f32_e32 v13, v13, v15
	v_max_f32_e64 v14, |v150|, |v150|
	v_max_f32_e32 v12, v12, v14
	v_max_f32_e64 v15, |v151|, |v151|
	v_max_f32_e32 v13, v13, v15
	s_waitcnt vmcnt(16)
	v_max_f32_e64 v14, |v152|, |v152|
	v_max_f32_e32 v12, v12, v14
	v_max_f32_e64 v15, |v153|, |v153|
	v_max_f32_e32 v13, v13, v15
	v_max_f32_e64 v14, |v154|, |v154|
	v_max_f32_e32 v12, v12, v14
	v_max_f32_e64 v15, |v155|, |v155|
	v_max_f32_e32 v13, v13, v15
	v_max_f32_e64 v14, |v156|, |v156|
	v_max_f32_e32 v12, v12, v14
	v_max_f32_e64 v15, |v157|, |v157|
	v_max_f32_e32 v13, v13, v15
	v_max_f32_e64 v14, |v158|, |v158|
	v_max_f32_e32 v12, v12, v14
	v_max_f32_e64 v15, |v159|, |v159|
	v_max_f32_e32 v13, v13, v15
	v_max_f32_e64 v14, |v160|, |v160|
	v_max_f32_e32 v12, v12, v14
	v_max_f32_e64 v15, |v161|, |v161|
	v_max_f32_e32 v13, v13, v15
	v_max_f32_e64 v14, |v162|, |v162|
	v_max_f32_e32 v12, v12, v14
	v_max_f32_e64 v15, |v163|, |v163|
	v_max_f32_e32 v13, v13, v15
	v_max_f32_e64 v14, |v164|, |v164|
	v_max_f32_e32 v12, v12, v14
	v_max_f32_e64 v15, |v165|, |v165|
	v_max_f32_e32 v13, v13, v15
	v_max_f32_e64 v14, |v166|, |v166|
	v_max_f32_e32 v12, v12, v14
	v_max_f32_e64 v15, |v167|, |v167|
	v_max_f32_e32 v13, v13, v15
	s_waitcnt vmcnt(0)
	v_max_f32_e64 v14, |v168|, |v168|
	v_max_f32_e32 v12, v12, v14
	v_max_f32_e64 v15, |v169|, |v169|
	v_max_f32_e32 v13, v13, v15
	v_max_f32_e64 v14, |v170|, |v170|
	v_max_f32_e32 v12, v12, v14
	v_max_f32_e64 v15, |v171|, |v171|
	v_max_f32_e32 v13, v13, v15
	v_max_f32_e64 v14, |v172|, |v172|
	v_max_f32_e32 v12, v12, v14
	v_max_f32_e64 v15, |v173|, |v173|
	v_max_f32_e32 v13, v13, v15
	v_max_f32_e64 v14, |v174|, |v174|
	v_max_f32_e32 v12, v12, v14
	v_max_f32_e64 v15, |v175|, |v175|
	v_max_f32_e32 v13, v13, v15
	v_max_f32_e64 v14, |v176|, |v176|
	v_max_f32_e32 v12, v12, v14
	v_max_f32_e64 v15, |v177|, |v177|
	v_max_f32_e32 v13, v13, v15
	v_max_f32_e64 v14, |v178|, |v178|
	v_max_f32_e32 v12, v12, v14
	v_max_f32_e64 v15, |v179|, |v179|
	v_max_f32_e32 v13, v13, v15
	v_max_f32_e64 v14, |v180|, |v180|
	v_max_f32_e32 v12, v12, v14
	v_max_f32_e64 v15, |v181|, |v181|
	v_max_f32_e32 v13, v13, v15
	v_max_f32_e64 v14, |v182|, |v182|
	v_max_f32_e32 v12, v12, v14
	v_max_f32_e64 v15, |v183|, |v183|
	v_max_f32_e32 v13, v13, v15
	s_mov_b64 s[10:11], 0
	s_mov_b64 s[6:7], exec
	v_mov_b32_e32 v2, 0
	v_mov_b32_e32 v14, 0
	v_mov_b32_e32 v15, 0
